# stack: conv_run loads issued earlier + gain deferral; epilogue loads hoisted / ring-prefetched (P0,P6,P7,P9)
# speedup vs baseline: 1.0044x; 1.0044x over previous
.LBB0_155:
	v_lshlrev_b32_e32 v161, 2, v0
	s_mov_b32 s1, 0
	s_waitcnt vmcnt(4)
	v_and_b32_e32 v4, 0x7c, v161
	v_lshl_add_u64 v[2:3], s[0:1], 2, v[2:3]
	v_mov_b32_e32 v37, 0
	v_lshlrev_b32_e32 v36, 2, v4
	v_lshl_add_u64 v[2:3], v[2:3], 0, v[36:37]
	v_lshl_add_u64 v[10:11], s[4:5], 2, v[2:3]
	global_load_dwordx4 v[2:5], v[2:3], off
	s_nop 0
	global_load_dwordx4 v[6:9], v[10:11], off
	v_mov_b32_e32 v64, 1.0
	v_mov_b32_e32 v65, 1.0
	v_mov_b32_e32 v66, 1.0
	v_mov_b32_e32 v67, 1.0
	v_mov_b32_e32 v68, 1.0
	v_mov_b32_e32 v69, 1.0
	v_mov_b32_e32 v70, 1.0
	v_mov_b32_e32 v71, 1.0
	v_cmp_ne_u64_e32 vcc, 0, v[38:39]
	s_and_saveexec_b64 s[10:11], vcc
	s_cbranch_execz .LBB0_157
	global_load_dwordx2 v[64:65], v[38:39], off
.LBB0_157:
	s_or_b64 exec, exec, s[10:11]
	s_mul_i32 s0, s4, 0x7c
	v_lshl_add_u64 v[10:11], v[10:11], 0, s[0:1]
	s_lshl_b64 s[4:5], s[4:5], 2
	v_lshl_add_u64 v[18:19], v[10:11], 0, s[4:5]
	global_load_dwordx4 v[10:13], v[10:11], off
	s_nop 0
	global_load_dwordx4 v[14:17], v[18:19], off
	s_and_saveexec_b64 s[10:11], vcc
	s_cbranch_execz .LBB0_159
	global_load_dwordx2 v[66:67], v[38:39], off offset:128
.LBB0_159:
	s_or_b64 exec, exec, s[10:11]
	v_lshl_add_u64 v[18:19], v[18:19], 0, s[0:1]
	v_lshl_add_u64 v[26:27], v[18:19], 0, s[4:5]
	global_load_dwordx4 v[18:21], v[18:19], off
	s_nop 0
	global_load_dwordx4 v[22:25], v[26:27], off
	s_and_saveexec_b64 s[10:11], vcc
	s_cbranch_execz .LBB0_161
	global_load_dwordx2 v[68:69], v[38:39], off offset:256
.LBB0_161:
	s_or_b64 exec, exec, s[10:11]
	v_lshl_add_u64 v[26:27], v[26:27], 0, s[0:1]
	v_lshl_add_u64 v[30:31], v[26:27], 0, s[4:5]
	global_load_dwordx4 v[26:29], v[26:27], off
	s_nop 0
	global_load_dwordx4 v[30:33], v[30:31], off
	s_and_saveexec_b64 s[0:1], vcc
	s_cbranch_execz .LBB0_163
	global_load_dwordx2 v[70:71], v[38:39], off offset:384

.LBB0_164:
	s_waitcnt vmcnt(0)
	v_mov_b64_e32 v[72:73], v[2:3]
	v_mov_b64_e32 v[74:75], v[4:5]
	v_mov_b64_e32 v[76:77], v[6:7]
	v_mov_b64_e32 v[78:79], v[8:9]
	v_mov_b64_e32 v[80:81], v[10:11]
	v_mov_b64_e32 v[82:83], v[12:13]
	v_mov_b64_e32 v[84:85], v[14:15]
	v_mov_b64_e32 v[86:87], v[16:17]
	v_mov_b64_e32 v[88:89], v[18:19]
	v_mov_b64_e32 v[90:91], v[20:21]
	v_mov_b64_e32 v[92:93], v[22:23]
	v_mov_b64_e32 v[94:95], v[24:25]
	v_mov_b64_e32 v[96:97], v[26:27]
	v_mov_b64_e32 v[98:99], v[28:29]
	v_mov_b64_e32 v[100:101], v[30:31]
	v_mov_b64_e32 v[102:103], v[32:33]
	v_mov_b64_e32 v[104:105], v[64:65]
	v_mov_b64_e32 v[106:107], v[66:67]
	v_mov_b64_e32 v[108:109], v[68:69]
	v_mov_b64_e32 v[110:111], v[70:71]
	s_add_i32 s10, s33, s38
	s_cmp_ge_i32 s10, s34
	s_cbranch_scc1 .LBB0_189
	s_cmpk_gt_i32 s10, 0xfe
	s_mov_b64 s[30:31], -1
	s_cbranch_scc0 .LBB0_178
	s_cmpk_gt_u32 s10, 0x4fe
	s_mov_b64 s[28:29], -1
	s_cbranch_scc0 .LBB0_176
	s_cmpk_gt_u32 s10, 0x8fe
	s_cbranch_scc0 .LBB0_173
	s_and_b32 s3, s35, 0x780
	s_cmpk_gt_u32 s10, 0x91e
	v_or_b32_e32 v4, s3, v1
	s_mov_b64 s[26:27], -1
	s_cbranch_scc0 .LBB0_170
	s_and_b32 s10, s36, 0xffffff80
	v_lshlrev_b32_e32 v2, 12, v4
	v_mov_b32_e32 v3, v37
	s_addk_i32 s10, 0xb700
	v_lshl_add_u64 v[2:3], s[12:13], 0, v[2:3]
	v_lshl_add_u64 v[2:3], s[10:11], 1, v[2:3]
	v_lshlrev_b32_e32 v6, 1, v38
	v_mov_b32_e32 v7, v37
	v_lshl_add_u64 v[42:43], v[2:3], 0, v[6:7]
	v_or_b32_e32 v2, s10, v46
	v_mov_b32_e32 v3, v37
	v_lshlrev_b64 v[2:3], 13, v[2:3]
	v_lshl_add_u64 v[2:3], s[76:77], 0, v[2:3]
	s_lshl_b32 s10, s3, 2
	v_lshl_add_u64 v[2:3], v[2:3], 0, s[10:11]
	s_mov_b64 s[26:27], 0

.LBB0_180:
	v_lshl_add_u64 v[2:3], v[2:3], 0, v[36:37]
	v_lshl_add_u64 v[10:11], s[28:29], 2, v[2:3]
	global_load_dwordx4 v[2:5], v[2:3], off
	s_nop 0
	global_load_dwordx4 v[6:9], v[10:11], off
	v_mov_b32_e32 v64, 1.0
	v_mov_b32_e32 v65, 1.0
	v_mov_b32_e32 v66, 1.0
	v_mov_b32_e32 v67, 1.0
	v_mov_b32_e32 v68, 1.0
	v_mov_b32_e32 v69, 1.0
	v_mov_b32_e32 v70, 1.0
	v_mov_b32_e32 v71, 1.0
	v_cmp_ne_u64_e32 vcc, 0, v[44:45]
	s_and_saveexec_b64 s[30:31], vcc
	s_cbranch_execz .LBB0_182
	global_load_dwordx2 v[64:65], v[44:45], off
.LBB0_182:
	s_or_b64 exec, exec, s[30:31]
	s_mul_i32 s10, s28, 0x7c
	v_lshl_add_u64 v[10:11], v[10:11], 0, s[10:11]
	s_lshl_b64 s[28:29], s[28:29], 2
	v_lshl_add_u64 v[18:19], v[10:11], 0, s[28:29]
	global_load_dwordx4 v[10:13], v[10:11], off
	s_nop 0
	global_load_dwordx4 v[14:17], v[18:19], off
	s_and_saveexec_b64 s[30:31], vcc
	s_cbranch_execz .LBB0_184
	global_load_dwordx2 v[66:67], v[44:45], off offset:128
.LBB0_184:
	s_or_b64 exec, exec, s[30:31]
	v_lshl_add_u64 v[18:19], v[18:19], 0, s[10:11]
	v_lshl_add_u64 v[26:27], v[18:19], 0, s[28:29]
	global_load_dwordx4 v[18:21], v[18:19], off
	s_nop 0
	global_load_dwordx4 v[22:25], v[26:27], off
	s_and_saveexec_b64 s[30:31], vcc
	s_cbranch_execz .LBB0_186
	global_load_dwordx2 v[68:69], v[44:45], off offset:256
.LBB0_186:
	s_or_b64 exec, exec, s[30:31]
	v_lshl_add_u64 v[26:27], v[26:27], 0, s[10:11]
	v_lshl_add_u64 v[30:31], v[26:27], 0, s[28:29]
	global_load_dwordx4 v[26:29], v[26:27], off
	s_nop 0
	global_load_dwordx4 v[30:33], v[30:31], off
	s_and_saveexec_b64 s[28:29], vcc
	s_cbranch_execz .LBB0_188
	global_load_dwordx2 v[70:71], v[44:45], off offset:384

.Lcvt_hb:
	v_pk_mul_f32 v[74:75], v[74:75], v[104:105] op_sel_hi:[1,0]
	v_pk_mul_f32 v[72:73], v[72:73], v[104:105] op_sel_hi:[1,0]
	v_pk_mul_f32 v[78:79], v[78:79], v[104:105] op_sel:[0,1]
	v_pk_mul_f32 v[76:77], v[76:77], v[104:105] op_sel:[0,1]
	v_pk_mul_f32 v[82:83], v[82:83], v[106:107] op_sel_hi:[1,0]
	v_pk_mul_f32 v[80:81], v[80:81], v[106:107] op_sel_hi:[1,0]
	v_pk_mul_f32 v[86:87], v[86:87], v[106:107] op_sel:[0,1]
	v_pk_mul_f32 v[84:85], v[84:85], v[106:107] op_sel:[0,1]
	v_pk_mul_f32 v[90:91], v[90:91], v[108:109] op_sel_hi:[1,0]
	v_pk_mul_f32 v[88:89], v[88:89], v[108:109] op_sel_hi:[1,0]
	v_pk_mul_f32 v[94:95], v[94:95], v[108:109] op_sel:[0,1]
	v_pk_mul_f32 v[92:93], v[92:93], v[108:109] op_sel:[0,1]
	v_pk_mul_f32 v[98:99], v[98:99], v[110:111] op_sel_hi:[1,0]
	v_pk_mul_f32 v[96:97], v[96:97], v[110:111] op_sel_hi:[1,0]
	v_pk_mul_f32 v[102:103], v[102:103], v[110:111] op_sel:[0,1]
	v_pk_mul_f32 v[100:101], v[100:101], v[110:111] op_sel:[0,1]
	v_cvt_pk_bf16_f32 v112, v72, v76
	v_cvt_pk_bf16_f32 v113, v73, v77
	ds_write2st64_b32 v50, v112, v113 offset1:1
	v_cvt_pk_bf16_f32 v112, v74, v78
	v_cvt_pk_bf16_f32 v113, v75, v79
	ds_write2st64_b32 v50, v112, v113 offset0:2 offset1:3
	v_cvt_pk_bf16_f32 v112, v80, v84
	v_cvt_pk_bf16_f32 v113, v81, v85
	ds_write2st64_b32 v49, v112, v113 offset1:1
	v_cvt_pk_bf16_f32 v112, v82, v86
	v_cvt_pk_bf16_f32 v113, v83, v87
	ds_write2st64_b32 v49, v112, v113 offset0:2 offset1:3
	v_cvt_pk_bf16_f32 v112, v88, v92
	v_cvt_pk_bf16_f32 v113, v89, v93
	ds_write2st64_b32 v48, v112, v113 offset1:1
	v_cvt_pk_bf16_f32 v112, v90, v94
	v_cvt_pk_bf16_f32 v113, v91, v95
	ds_write2st64_b32 v48, v112, v113 offset0:2 offset1:3
	v_cvt_pk_bf16_f32 v112, v96, v100
	v_cvt_pk_bf16_f32 v113, v97, v101
	ds_write2st64_b32 v39, v112, v113 offset1:1
	v_cvt_pk_bf16_f32 v112, v98, v102
	v_cvt_pk_bf16_f32 v113, v99, v103
	ds_write2st64_b32 v39, v112, v113 offset0:2 offset1:3
	s_waitcnt lgkmcnt(0)
	s_barrier

.LBB0_193:
	s_waitcnt vmcnt(4)
	v_pk_mul_f32 v[4:5], v[4:5], v[64:65] op_sel_hi:[1,0]
	v_pk_mul_f32 v[2:3], v[2:3], v[64:65] op_sel_hi:[1,0]
	v_pk_mul_f32 v[8:9], v[8:9], v[64:65] op_sel:[0,1]
	v_pk_mul_f32 v[6:7], v[6:7], v[64:65] op_sel:[0,1]
	v_pk_mul_f32 v[12:13], v[12:13], v[66:67] op_sel_hi:[1,0]
	v_pk_mul_f32 v[10:11], v[10:11], v[66:67] op_sel_hi:[1,0]
	v_pk_mul_f32 v[16:17], v[16:17], v[66:67] op_sel:[0,1]
	v_pk_mul_f32 v[14:15], v[14:15], v[66:67] op_sel:[0,1]
	v_pk_mul_f32 v[20:21], v[20:21], v[68:69] op_sel_hi:[1,0]
	v_pk_mul_f32 v[18:19], v[18:19], v[68:69] op_sel_hi:[1,0]
	v_pk_mul_f32 v[24:25], v[24:25], v[68:69] op_sel:[0,1]
	v_pk_mul_f32 v[22:23], v[22:23], v[68:69] op_sel:[0,1]
	v_pk_mul_f32 v[28:29], v[28:29], v[70:71] op_sel_hi:[1,0]
	v_pk_mul_f32 v[26:27], v[26:27], v[70:71] op_sel_hi:[1,0]
	v_pk_mul_f32 v[32:33], v[32:33], v[70:71] op_sel:[0,1]
	v_pk_mul_f32 v[30:31], v[30:31], v[70:71] op_sel:[0,1]
	v_cvt_pk_bf16_f32 v2, v2, v6
	v_cvt_pk_bf16_f32 v3, v3, v7
	ds_write2st64_b32 v50, v2, v3 offset1:1
	v_cvt_pk_bf16_f32 v2, v4, v8
	v_cvt_pk_bf16_f32 v3, v5, v9
	ds_write2st64_b32 v50, v2, v3 offset0:2 offset1:3
	s_waitcnt vmcnt(8)
	v_cvt_pk_bf16_f32 v2, v10, v14
	v_cvt_pk_bf16_f32 v3, v11, v15
	ds_write2st64_b32 v49, v2, v3 offset1:1
	v_cvt_pk_bf16_f32 v2, v12, v16
	v_cvt_pk_bf16_f32 v3, v13, v17
	ds_write2st64_b32 v49, v2, v3 offset0:2 offset1:3
	s_waitcnt vmcnt(6)
	v_cvt_pk_bf16_f32 v2, v18, v22
	v_cvt_pk_bf16_f32 v3, v19, v23
	ds_write2st64_b32 v48, v2, v3 offset1:1
	v_cvt_pk_bf16_f32 v2, v20, v24
	v_cvt_pk_bf16_f32 v3, v21, v25
	ds_write2st64_b32 v48, v2, v3 offset0:2 offset1:3
	s_waitcnt vmcnt(4)
	v_cvt_pk_bf16_f32 v2, v26, v30
	v_cvt_pk_bf16_f32 v3, v27, v31
	ds_write2st64_b32 v39, v2, v3 offset1:1
	v_cvt_pk_bf16_f32 v2, v28, v32
	v_cvt_pk_bf16_f32 v3, v29, v33
	ds_write2st64_b32 v39, v2, v3 offset0:2 offset1:3
	s_waitcnt lgkmcnt(0)
	s_barrier
	ds_read_b128 v[2:5], v53
	ds_read_b128 v[6:9], v52
	s_mov_b32 s27, 0
	s_lshl_b64 s[2:3], s[26:27], 6
	s_waitcnt lgkmcnt(1)
	v_cndmask_b32_e64 v10, v3, v2, s[4:5]
	v_cndmask_b32_e64 v11, v2, v3, s[4:5]
	v_cndmask_b32_e64 v12, v5, v4, s[4:5]
	v_cndmask_b32_e64 v5, v4, v5, s[4:5]
	v_cndmask_b32_e64 v2, v12, v10, s[0:1]
	v_cndmask_b32_e64 v3, v5, v11, s[0:1]
	v_cndmask_b32_e64 v4, v10, v12, s[0:1]
	v_cndmask_b32_e64 v5, v11, v5, s[0:1]
	global_store_dwordx4 v[42:43], v[2:5], off
	v_lshl_add_u64 v[10:11], v[42:43], 0, s[2:3]
	s_waitcnt lgkmcnt(0)
	v_cndmask_b32_e64 v4, v7, v6, s[4:5]
	v_cndmask_b32_e64 v5, v6, v7, s[4:5]
	v_cndmask_b32_e64 v6, v9, v8, s[4:5]
	v_cndmask_b32_e64 v7, v8, v9, s[4:5]
	v_cndmask_b32_e64 v2, v6, v4, s[0:1]
	v_cndmask_b32_e64 v3, v7, v5, s[0:1]
	v_cndmask_b32_e64 v4, v4, v6, s[0:1]
	v_cndmask_b32_e64 v5, v5, v7, s[0:1]
	ds_read_b128 v[6:9], v51
	global_store_dwordx4 v[10:11], v[2:5], off
	ds_read_b128 v[2:5], v47
	v_lshl_add_u64 v[10:11], v[10:11], 0, s[2:3]
	s_waitcnt lgkmcnt(1)
	v_cndmask_b32_e64 v12, v7, v6, s[4:5]
	v_cndmask_b32_e64 v13, v6, v7, s[4:5]
	v_cndmask_b32_e64 v14, v9, v8, s[4:5]
	v_cndmask_b32_e64 v9, v8, v9, s[4:5]
	v_cndmask_b32_e64 v6, v14, v12, s[0:1]
	v_cndmask_b32_e64 v7, v9, v13, s[0:1]
	v_cndmask_b32_e64 v8, v12, v14, s[0:1]
	v_cndmask_b32_e64 v9, v13, v9, s[0:1]
	global_store_dwordx4 v[10:11], v[6:9], off
	s_waitcnt lgkmcnt(0)
	s_nop 0
	v_cndmask_b32_e64 v6, v3, v2, s[4:5]
	v_cndmask_b32_e64 v7, v2, v3, s[4:5]
	v_cndmask_b32_e64 v8, v5, v4, s[4:5]
	v_cndmask_b32_e64 v5, v4, v5, s[4:5]
	v_cndmask_b32_e64 v2, v8, v6, s[0:1]
	v_cndmask_b32_e64 v3, v5, v7, s[0:1]
	v_cndmask_b32_e64 v4, v6, v8, s[0:1]
	v_cndmask_b32_e64 v5, v7, v5, s[0:1]
	v_lshl_add_u64 v[6:7], v[10:11], 0, s[2:3]
	global_store_dwordx4 v[6:7], v[2:5], off
	s_barrier
	s_branch .LBB0_195

.Lcvt_la:
	v_cvt_pk_bf16_f32 v112, v72, v76
	v_cvt_pk_bf16_f32 v113, v73, v77
	ds_write2st64_b32 v46, v112, v113 offset1:1
	v_cvt_pk_bf16_f32 v112, v74, v78
	v_cvt_pk_bf16_f32 v113, v75, v79
	ds_write2st64_b32 v46, v112, v113 offset0:2 offset1:3
	v_cvt_pk_bf16_f32 v112, v80, v84
	v_cvt_pk_bf16_f32 v113, v81, v85
	ds_write2st64_b32 v47, v112, v113 offset1:1
	v_cvt_pk_bf16_f32 v112, v82, v86
	v_cvt_pk_bf16_f32 v113, v83, v87
	ds_write2st64_b32 v47, v112, v113 offset0:2 offset1:3
	v_cvt_pk_bf16_f32 v112, v88, v92
	v_cvt_pk_bf16_f32 v113, v89, v93
	ds_write2st64_b32 v48, v112, v113 offset1:1
	v_cvt_pk_bf16_f32 v112, v90, v94
	v_cvt_pk_bf16_f32 v113, v91, v95
	ds_write2st64_b32 v48, v112, v113 offset0:2 offset1:3
	v_cvt_pk_bf16_f32 v112, v96, v100
	v_cvt_pk_bf16_f32 v113, v97, v101
	ds_write2st64_b32 v49, v112, v113 offset1:1
	v_cvt_pk_bf16_f32 v112, v98, v102
	v_cvt_pk_bf16_f32 v113, v99, v103
	ds_write2st64_b32 v49, v112, v113 offset0:2 offset1:3
	s_waitcnt lgkmcnt(0)
	s_barrier

.LBB0_409:
	s_waitcnt vmcnt(0)
	v_mov_b64_e32 v[72:73], v[2:3]
	v_mov_b64_e32 v[74:75], v[4:5]
	v_mov_b64_e32 v[76:77], v[6:7]
	v_mov_b64_e32 v[78:79], v[8:9]
	v_mov_b64_e32 v[80:81], v[10:11]
	v_mov_b64_e32 v[82:83], v[12:13]
	v_mov_b64_e32 v[84:85], v[14:15]
	v_mov_b64_e32 v[86:87], v[16:17]
	v_mov_b64_e32 v[88:89], v[18:19]
	v_mov_b64_e32 v[90:91], v[20:21]
	v_mov_b64_e32 v[92:93], v[22:23]
	v_mov_b64_e32 v[94:95], v[24:25]
	v_mov_b64_e32 v[96:97], v[26:27]
	v_mov_b64_e32 v[98:99], v[28:29]
	v_mov_b64_e32 v[100:101], v[30:31]
	v_mov_b64_e32 v[102:103], v[32:33]
	s_add_i32 s35, s3, 1
	s_cmp_ge_i32 s35, s30
	s_cselect_b64 s[24:25], -1, 0
	s_and_b64 vcc, exec, s[24:25]
	s_mov_b32 s36, s2
	s_cbranch_vccnz .Lcvt_la
	s_cmpk_gt_i32 s3, 0xfe
	s_mov_b64 s[28:29], -1
	s_cbranch_scc0 .LBB0_423
	s_cmpk_gt_u32 s35, 0x4ff
	s_mov_b64 s[26:27], -1
	s_cbranch_scc0 .LBB0_421
	s_cmpk_gt_u32 s35, 0x8ff
	s_cbranch_scc0 .LBB0_418
	s_and_b32 s3, s33, 0x780
	s_cmpk_gt_u32 s35, 0x91f
	v_or_b32_e32 v4, s3, v1
	s_cbranch_scc0 .LBB0_415
	s_and_b32 s8, s31, 0xffffff80
	v_lshlrev_b32_e32 v2, 12, v4
	v_mov_b32_e32 v3, v39
	s_addk_i32 s8, 0xb700
	v_lshl_add_u64 v[2:3], s[10:11], 0, v[2:3]
	v_lshl_add_u64 v[2:3], s[8:9], 1, v[2:3]
	v_lshlrev_b32_e32 v6, 1, v36
	v_mov_b32_e32 v7, v39
	v_lshl_add_u64 v[42:43], v[2:3], 0, v[6:7]
	v_or_b32_e32 v2, s8, v37
	v_mov_b32_e32 v3, v39
	v_lshlrev_b64 v[2:3], 13, v[2:3]
	v_lshl_add_u64 v[2:3], s[76:77], 0, v[2:3]
	s_lshl_b32 s8, s3, 2
	v_lshl_add_u64 v[2:3], v[2:3], 0, s[8:9]
	s_mov_b64 s[26:27], 0

.LBB0_448:
	s_mov_b32 s1, 0
	s_waitcnt vmcnt(11)
	v_and_b32_e32 v4, 0x7c, v161
	v_lshl_add_u64 v[2:3], s[0:1], 2, v[2:3]
	v_mov_b32_e32 v37, 0
	v_lshlrev_b32_e32 v36, 2, v4
	v_lshl_add_u64 v[2:3], v[2:3], 0, v[36:37]
	s_waitcnt vmcnt(9)
	v_lshl_add_u64 v[10:11], s[4:5], 2, v[2:3]
	global_load_dwordx4 v[2:5], v[2:3], off
	s_nop 0
	global_load_dwordx4 v[6:9], v[10:11], off
	v_mov_b32_e32 v64, 1.0
	v_mov_b32_e32 v65, 1.0
	v_mov_b32_e32 v66, 1.0
	v_mov_b32_e32 v67, 1.0
	v_mov_b32_e32 v68, 1.0
	v_mov_b32_e32 v69, 1.0
	v_mov_b32_e32 v70, 1.0
	v_mov_b32_e32 v71, 1.0
	v_cmp_ne_u64_e32 vcc, 0, v[38:39]
	s_and_saveexec_b64 s[6:7], vcc
	s_cbranch_execz .LBB0_450
	global_load_dwordx2 v[64:65], v[38:39], off
.LBB0_450:
	s_or_b64 exec, exec, s[6:7]
	s_mul_i32 s0, s4, 0x7c
	v_lshl_add_u64 v[10:11], v[10:11], 0, s[0:1]
	s_lshl_b64 s[4:5], s[4:5], 2
	s_waitcnt vmcnt(9)
	v_lshl_add_u64 v[18:19], v[10:11], 0, s[4:5]
	global_load_dwordx4 v[10:13], v[10:11], off
	s_nop 0
	global_load_dwordx4 v[14:17], v[18:19], off
	s_and_saveexec_b64 s[6:7], vcc
	s_cbranch_execz .LBB0_452
	global_load_dwordx2 v[66:67], v[38:39], off offset:128
.LBB0_452:
	s_or_b64 exec, exec, s[6:7]
	v_lshl_add_u64 v[18:19], v[18:19], 0, s[0:1]
	s_waitcnt vmcnt(9)
	v_lshl_add_u64 v[26:27], v[18:19], 0, s[4:5]
	global_load_dwordx4 v[18:21], v[18:19], off
	s_nop 0
	global_load_dwordx4 v[22:25], v[26:27], off
	s_and_saveexec_b64 s[6:7], vcc
	s_cbranch_execz .LBB0_454
	global_load_dwordx2 v[68:69], v[38:39], off offset:256
.LBB0_454:
	s_or_b64 exec, exec, s[6:7]
	v_lshl_add_u64 v[26:27], v[26:27], 0, s[0:1]
	s_waitcnt vmcnt(10)
	v_lshl_add_u64 v[30:31], v[26:27], 0, s[4:5]
	global_load_dwordx4 v[26:29], v[26:27], off
	s_nop 0
	global_load_dwordx4 v[30:33], v[30:31], off
	s_and_saveexec_b64 s[0:1], vcc
	s_cbranch_execz .LBB0_456
	global_load_dwordx2 v[70:71], v[38:39], off offset:384

.LBB0_457:
	s_waitcnt vmcnt(0)
	v_mov_b64_e32 v[72:73], v[2:3]
	v_mov_b64_e32 v[74:75], v[4:5]
	v_mov_b64_e32 v[76:77], v[6:7]
	v_mov_b64_e32 v[78:79], v[8:9]
	v_mov_b64_e32 v[80:81], v[10:11]
	v_mov_b64_e32 v[82:83], v[12:13]
	v_mov_b64_e32 v[84:85], v[14:15]
	v_mov_b64_e32 v[86:87], v[16:17]
	v_mov_b64_e32 v[88:89], v[18:19]
	v_mov_b64_e32 v[90:91], v[20:21]
	v_mov_b64_e32 v[92:93], v[22:23]
	v_mov_b64_e32 v[94:95], v[24:25]
	v_mov_b64_e32 v[96:97], v[26:27]
	v_mov_b64_e32 v[98:99], v[28:29]
	v_mov_b64_e32 v[100:101], v[30:31]
	v_mov_b64_e32 v[102:103], v[32:33]
	v_mov_b64_e32 v[104:105], v[64:65]
	v_mov_b64_e32 v[106:107], v[66:67]
	v_mov_b64_e32 v[108:109], v[68:69]
	v_mov_b64_e32 v[110:111], v[70:71]
	s_add_i32 s6, s28, s34
	s_cmp_ge_i32 s6, s29
	s_cbranch_scc1 .LBB0_482
	s_cmpk_gt_i32 s6, 0xfe
	s_mov_b64 s[26:27], -1
	s_cbranch_scc0 .LBB0_471
	s_cmpk_gt_u32 s6, 0x4fe
	s_mov_b64 s[24:25], -1
	s_cbranch_scc0 .LBB0_469
	s_cmpk_gt_u32 s6, 0x8fe
	s_cbranch_scc0 .LBB0_466
	s_and_b32 s3, s30, 0x780
	s_cmpk_gt_u32 s6, 0x91e
	v_or_b32_e32 v4, s3, v1
	s_mov_b64 s[22:23], -1
	s_cbranch_scc0 .LBB0_463
	s_and_b32 s6, s31, 0xffffff80
	v_lshlrev_b32_e32 v2, 12, v4
	v_mov_b32_e32 v3, v37
	s_addk_i32 s6, 0xb700
	v_lshl_add_u64 v[2:3], s[8:9], 0, v[2:3]
	v_lshl_add_u64 v[2:3], s[6:7], 1, v[2:3]
	v_lshlrev_b32_e32 v6, 1, v38
	v_mov_b32_e32 v7, v37
	v_lshl_add_u64 v[42:43], v[2:3], 0, v[6:7]
	v_or_b32_e32 v2, s6, v48
	v_mov_b32_e32 v3, v37
	v_lshlrev_b64 v[2:3], 13, v[2:3]
	v_lshl_add_u64 v[2:3], s[76:77], 0, v[2:3]
	s_lshl_b32 s6, s3, 2
	v_lshl_add_u64 v[2:3], v[2:3], 0, s[6:7]
	s_mov_b64 s[22:23], 0

.LBB0_473:
	v_lshl_add_u64 v[2:3], v[2:3], 0, v[36:37]
	v_lshl_add_u64 v[10:11], s[24:25], 2, v[2:3]
	global_load_dwordx4 v[2:5], v[2:3], off
	s_nop 0
	global_load_dwordx4 v[6:9], v[10:11], off
	v_mov_b32_e32 v64, 1.0
	v_mov_b32_e32 v65, 1.0
	v_mov_b32_e32 v66, 1.0
	v_mov_b32_e32 v67, 1.0
	v_mov_b32_e32 v68, 1.0
	v_mov_b32_e32 v69, 1.0
	v_mov_b32_e32 v70, 1.0
	v_mov_b32_e32 v71, 1.0
	v_cmp_ne_u64_e32 vcc, 0, v[44:45]
	s_and_saveexec_b64 s[26:27], vcc
	s_cbranch_execz .LBB0_475
	global_load_dwordx2 v[64:65], v[44:45], off
.LBB0_475:
	s_or_b64 exec, exec, s[26:27]
	s_mul_i32 s6, s24, 0x7c
	v_lshl_add_u64 v[10:11], v[10:11], 0, s[6:7]
	s_lshl_b64 s[24:25], s[24:25], 2
	v_lshl_add_u64 v[18:19], v[10:11], 0, s[24:25]
	global_load_dwordx4 v[10:13], v[10:11], off
	s_nop 0
	global_load_dwordx4 v[14:17], v[18:19], off
	s_and_saveexec_b64 s[26:27], vcc
	s_cbranch_execz .LBB0_477
	global_load_dwordx2 v[66:67], v[44:45], off offset:128
.LBB0_477:
	s_or_b64 exec, exec, s[26:27]
	v_lshl_add_u64 v[18:19], v[18:19], 0, s[6:7]
	v_lshl_add_u64 v[26:27], v[18:19], 0, s[24:25]
	global_load_dwordx4 v[18:21], v[18:19], off
	s_nop 0
	global_load_dwordx4 v[22:25], v[26:27], off
	s_and_saveexec_b64 s[26:27], vcc
	s_cbranch_execz .LBB0_479
	global_load_dwordx2 v[68:69], v[44:45], off offset:256
.LBB0_479:
	s_or_b64 exec, exec, s[26:27]
	v_lshl_add_u64 v[26:27], v[26:27], 0, s[6:7]
	v_lshl_add_u64 v[30:31], v[26:27], 0, s[24:25]
	global_load_dwordx4 v[26:29], v[26:27], off
	s_nop 0
	global_load_dwordx4 v[30:33], v[30:31], off
	s_and_saveexec_b64 s[24:25], vcc
	s_cbranch_execz .LBB0_481
	global_load_dwordx2 v[70:71], v[44:45], off offset:384

.Lcvt_ha:
	v_pk_mul_f32 v[74:75], v[74:75], v[104:105] op_sel_hi:[1,0]
	v_pk_mul_f32 v[72:73], v[72:73], v[104:105] op_sel_hi:[1,0]
	v_pk_mul_f32 v[78:79], v[78:79], v[104:105] op_sel:[0,1]
	v_pk_mul_f32 v[76:77], v[76:77], v[104:105] op_sel:[0,1]
	v_pk_mul_f32 v[82:83], v[82:83], v[106:107] op_sel_hi:[1,0]
	v_pk_mul_f32 v[80:81], v[80:81], v[106:107] op_sel_hi:[1,0]
	v_pk_mul_f32 v[86:87], v[86:87], v[106:107] op_sel:[0,1]
	v_pk_mul_f32 v[84:85], v[84:85], v[106:107] op_sel:[0,1]
	v_pk_mul_f32 v[90:91], v[90:91], v[108:109] op_sel_hi:[1,0]
	v_pk_mul_f32 v[88:89], v[88:89], v[108:109] op_sel_hi:[1,0]
	v_pk_mul_f32 v[94:95], v[94:95], v[108:109] op_sel:[0,1]
	v_pk_mul_f32 v[92:93], v[92:93], v[108:109] op_sel:[0,1]
	v_pk_mul_f32 v[98:99], v[98:99], v[110:111] op_sel_hi:[1,0]
	v_pk_mul_f32 v[96:97], v[96:97], v[110:111] op_sel_hi:[1,0]
	v_pk_mul_f32 v[102:103], v[102:103], v[110:111] op_sel:[0,1]
	v_pk_mul_f32 v[100:101], v[100:101], v[110:111] op_sel:[0,1]
	v_cvt_pk_bf16_f32 v112, v72, v76
	v_cvt_pk_bf16_f32 v113, v73, v77
	ds_write2st64_b32 v50, v112, v113 offset1:1
	v_cvt_pk_bf16_f32 v112, v74, v78
	v_cvt_pk_bf16_f32 v113, v75, v79
	ds_write2st64_b32 v50, v112, v113 offset0:2 offset1:3
	v_cvt_pk_bf16_f32 v112, v80, v84
	v_cvt_pk_bf16_f32 v113, v81, v85
	ds_write2st64_b32 v49, v112, v113 offset1:1
	v_cvt_pk_bf16_f32 v112, v82, v86
	v_cvt_pk_bf16_f32 v113, v83, v87
	ds_write2st64_b32 v49, v112, v113 offset0:2 offset1:3
	v_cvt_pk_bf16_f32 v112, v88, v92
	v_cvt_pk_bf16_f32 v113, v89, v93
	ds_write2st64_b32 v47, v112, v113 offset1:1
	v_cvt_pk_bf16_f32 v112, v90, v94
	v_cvt_pk_bf16_f32 v113, v91, v95
	ds_write2st64_b32 v47, v112, v113 offset0:2 offset1:3
	v_cvt_pk_bf16_f32 v112, v96, v100
	v_cvt_pk_bf16_f32 v113, v97, v101
	ds_write2st64_b32 v39, v112, v113 offset1:1
	v_cvt_pk_bf16_f32 v112, v98, v102
	v_cvt_pk_bf16_f32 v113, v99, v103
	ds_write2st64_b32 v39, v112, v113 offset0:2 offset1:3
	s_waitcnt lgkmcnt(0)
	s_barrier

.LBB0_486:
	s_waitcnt vmcnt(4)
	v_pk_mul_f32 v[4:5], v[4:5], v[64:65] op_sel_hi:[1,0]
	v_pk_mul_f32 v[2:3], v[2:3], v[64:65] op_sel_hi:[1,0]
	v_pk_mul_f32 v[8:9], v[8:9], v[64:65] op_sel:[0,1]
	v_pk_mul_f32 v[6:7], v[6:7], v[64:65] op_sel:[0,1]
	v_pk_mul_f32 v[12:13], v[12:13], v[66:67] op_sel_hi:[1,0]
	v_pk_mul_f32 v[10:11], v[10:11], v[66:67] op_sel_hi:[1,0]
	v_pk_mul_f32 v[16:17], v[16:17], v[66:67] op_sel:[0,1]
	v_pk_mul_f32 v[14:15], v[14:15], v[66:67] op_sel:[0,1]
	v_pk_mul_f32 v[20:21], v[20:21], v[68:69] op_sel_hi:[1,0]
	v_pk_mul_f32 v[18:19], v[18:19], v[68:69] op_sel_hi:[1,0]
	v_pk_mul_f32 v[24:25], v[24:25], v[68:69] op_sel:[0,1]
	v_pk_mul_f32 v[22:23], v[22:23], v[68:69] op_sel:[0,1]
	v_pk_mul_f32 v[28:29], v[28:29], v[70:71] op_sel_hi:[1,0]
	v_pk_mul_f32 v[26:27], v[26:27], v[70:71] op_sel_hi:[1,0]
	v_pk_mul_f32 v[32:33], v[32:33], v[70:71] op_sel:[0,1]
	v_pk_mul_f32 v[30:31], v[30:31], v[70:71] op_sel:[0,1]
	v_cvt_pk_bf16_f32 v2, v2, v6
	v_cvt_pk_bf16_f32 v3, v3, v7
	ds_write2st64_b32 v50, v2, v3 offset1:1
	v_cvt_pk_bf16_f32 v2, v4, v8
	v_cvt_pk_bf16_f32 v3, v5, v9
	ds_write2st64_b32 v50, v2, v3 offset0:2 offset1:3
	s_waitcnt vmcnt(8)
	v_cvt_pk_bf16_f32 v2, v10, v14
	v_cvt_pk_bf16_f32 v3, v11, v15
	ds_write2st64_b32 v49, v2, v3 offset1:1
	v_cvt_pk_bf16_f32 v2, v12, v16
	v_cvt_pk_bf16_f32 v3, v13, v17
	ds_write2st64_b32 v49, v2, v3 offset0:2 offset1:3
	s_waitcnt vmcnt(6)
	v_cvt_pk_bf16_f32 v2, v18, v22
	v_cvt_pk_bf16_f32 v3, v19, v23
	ds_write2st64_b32 v47, v2, v3 offset1:1
	v_cvt_pk_bf16_f32 v2, v20, v24
	v_cvt_pk_bf16_f32 v3, v21, v25
	ds_write2st64_b32 v47, v2, v3 offset0:2 offset1:3
	s_waitcnt vmcnt(4)
	v_cvt_pk_bf16_f32 v2, v26, v30
	v_cvt_pk_bf16_f32 v3, v27, v31
	ds_write2st64_b32 v39, v2, v3 offset1:1
	v_cvt_pk_bf16_f32 v2, v28, v32
	v_cvt_pk_bf16_f32 v3, v29, v33
	ds_write2st64_b32 v39, v2, v3 offset0:2 offset1:3
	s_waitcnt lgkmcnt(0)
	s_barrier
	ds_read_b128 v[2:5], v53
	ds_read_b128 v[6:9], v52
	s_mov_b32 s23, 0
	s_lshl_b64 s[2:3], s[22:23], 6
	s_waitcnt lgkmcnt(1)
	v_cndmask_b32_e64 v10, v3, v2, s[4:5]
	v_cndmask_b32_e64 v11, v2, v3, s[4:5]
	v_cndmask_b32_e64 v12, v5, v4, s[4:5]
	v_cndmask_b32_e64 v5, v4, v5, s[4:5]
	v_cndmask_b32_e64 v2, v12, v10, s[0:1]
	v_cndmask_b32_e64 v3, v5, v11, s[0:1]
	v_cndmask_b32_e64 v4, v10, v12, s[0:1]
	v_cndmask_b32_e64 v5, v11, v5, s[0:1]
	global_store_dwordx4 v[42:43], v[2:5], off
	v_lshl_add_u64 v[10:11], v[42:43], 0, s[2:3]
	s_waitcnt lgkmcnt(0)
	v_cndmask_b32_e64 v4, v7, v6, s[4:5]
	v_cndmask_b32_e64 v5, v6, v7, s[4:5]
	v_cndmask_b32_e64 v6, v9, v8, s[4:5]
	v_cndmask_b32_e64 v7, v8, v9, s[4:5]
	v_cndmask_b32_e64 v2, v6, v4, s[0:1]
	v_cndmask_b32_e64 v3, v7, v5, s[0:1]
	v_cndmask_b32_e64 v4, v4, v6, s[0:1]
	v_cndmask_b32_e64 v5, v5, v7, s[0:1]
	ds_read_b128 v[6:9], v51
	global_store_dwordx4 v[10:11], v[2:5], off
	ds_read_b128 v[2:5], v46
	v_lshl_add_u64 v[10:11], v[10:11], 0, s[2:3]
	s_waitcnt lgkmcnt(1)
	v_cndmask_b32_e64 v12, v7, v6, s[4:5]
	v_cndmask_b32_e64 v13, v6, v7, s[4:5]
	v_cndmask_b32_e64 v14, v9, v8, s[4:5]
	v_cndmask_b32_e64 v9, v8, v9, s[4:5]
	v_cndmask_b32_e64 v6, v14, v12, s[0:1]
	v_cndmask_b32_e64 v7, v9, v13, s[0:1]
	v_cndmask_b32_e64 v8, v12, v14, s[0:1]
	v_cndmask_b32_e64 v9, v13, v9, s[0:1]
	global_store_dwordx4 v[10:11], v[6:9], off
	s_waitcnt lgkmcnt(0)
	s_nop 0
	v_cndmask_b32_e64 v6, v3, v2, s[4:5]
	v_cndmask_b32_e64 v7, v2, v3, s[4:5]
	v_cndmask_b32_e64 v8, v5, v4, s[4:5]
	v_cndmask_b32_e64 v5, v4, v5, s[4:5]
	v_cndmask_b32_e64 v2, v8, v6, s[0:1]
	v_cndmask_b32_e64 v3, v5, v7, s[0:1]
	v_cndmask_b32_e64 v4, v6, v8, s[0:1]
	v_cndmask_b32_e64 v5, v7, v5, s[0:1]
	v_lshl_add_u64 v[6:7], v[10:11], 0, s[2:3]
	global_store_dwordx4 v[6:7], v[2:5], off
	s_barrier

.LBB0_1520:
	v_lshl_add_u32 v148, s22, 8, v151
	v_lshl_or_b32 v146, s24, 8, v153
	v_ashrrev_i32_e32 v149, 31, v148
	v_ashrrev_i32_e32 v147, 31, v146
	v_lshlrev_b64 v[158:159], 11, v[148:149]
	v_readlane_b32 s48, v254, 9
	v_lshl_add_u64 v[166:167], v[158:159], 0, v[146:147]
	v_readlane_b32 s49, v254, 10
	v_readlane_b32 s50, v254, 11
	v_readlane_b32 s51, v254, 12
	v_lshl_add_u64 v[168:169], v[166:167], 2, s[48:49]
	s_mov_b32 s98, 0x20000
	s_mov_b32 s99, 0
	s_mov_b32 s100, 0xa0000
	s_mov_b32 s101, 0
	v_mov_b32_e32 v208, v168
	v_mov_b32_e32 v209, v169
	global_load_dwordx4 v[176:179], v[208:209], off
	global_load_dwordx4 v[180:183], v[208:209], off offset:16
	global_load_dwordx4 v[184:187], v[208:209], off offset:512
	global_load_dwordx4 v[188:191], v[208:209], off offset:528
	v_lshl_add_u64 v[208:209], v[208:209], 0, s[98:99]
	global_load_dwordx4 v[192:195], v[208:209], off
	global_load_dwordx4 v[196:199], v[208:209], off offset:16
	global_load_dwordx4 v[200:203], v[208:209], off offset:512
	global_load_dwordx4 v[204:207], v[208:209], off offset:528
	v_lshl_add_u64 v[208:209], v[208:209], 0, s[98:99]
	global_load_dwordx4 v[214:217], v[208:209], off
	global_load_dwordx4 v[218:221], v[208:209], off offset:16
	v_lshlrev_b64 v[166:167], 1, v[166:167]
	v_lshl_add_u64 v[170:171], s[8:9], 0, v[166:167]
	v_or_b32_e32 v166, 0x100, v166
	v_readlane_b32 s52, v254, 13
	v_readlane_b32 s53, v254, 14
	v_readlane_b32 s54, v254, 15
	v_readlane_b32 s55, v254, 16
	v_readlane_b32 s56, v254, 17
	v_readlane_b32 s57, v254, 18
	v_readlane_b32 s58, v254, 19
	v_readlane_b32 s59, v254, 20
	v_readlane_b32 s60, v254, 21
	v_readlane_b32 s61, v254, 22
	v_readlane_b32 s62, v254, 23
	v_readlane_b32 s63, v254, 24
	s_waitcnt vmcnt(6)
	v_pk_add_f32 v[172:173], v[128:129], v[178:179]
	v_pk_add_f32 v[174:175], v[126:127], v[176:177]
	v_pk_add_f32 v[164:165], v[124:125], v[182:183]
	v_pk_add_f32 v[162:163], v[122:123], v[180:181]
	v_cvt_pk_bf16_f32 v122, v174, v175
	v_cvt_pk_bf16_f32 v123, v172, v173
	v_mul_f32_e32 v157, v175, v175
	v_cvt_pk_bf16_f32 v124, v162, v163
	v_cvt_pk_bf16_f32 v125, v164, v165
	global_store_dwordx4 v[170:171], v[122:125], off
	s_nop 1
	v_mul_f32_e32 v168, v173, v173
	v_and_b32_e32 v123, 64, v150
	v_mul_f32_e32 v163, v163, v163
	v_fmac_f32_e32 v157, v174, v174
	v_fmac_f32_e32 v168, v172, v172
	v_xor_b32_e32 v122, 16, v150
	v_add_u32_e32 v123, 64, v123
	v_mul_f32_e32 v165, v165, v165
	v_fmac_f32_e32 v163, v162, v162
	v_add_f32_e32 v157, v157, v168
	v_cmp_lt_i32_e32 vcc, v122, v123
	v_fmac_f32_e32 v165, v164, v164
	v_add_f32_e32 v157, v157, v163
	v_cndmask_b32_e32 v125, v150, v122, vcc
	v_add_f32_e32 v157, v165, v157
	v_lshlrev_b32_e32 v125, 2, v125
	v_xor_b32_e32 v124, 32, v150
	v_cmp_lt_i32_e32 vcc, v124, v123
	v_pk_add_f32 v[120:121], v[120:121], v[186:187]
	v_pk_add_f32 v[118:119], v[118:119], v[184:185]
	v_pk_add_f32 v[126:127], v[116:117], v[190:191]
	v_pk_add_f32 v[114:115], v[114:115], v[188:189]
	global_load_dwordx4 v[176:179], v[208:209], off offset:512
	global_load_dwordx4 v[180:183], v[208:209], off offset:528
	v_lshl_add_u64 v[208:209], v[208:209], 0, s[98:99]
	global_load_dwordx4 v[184:187], v[208:209], off
	global_load_dwordx4 v[188:191], v[208:209], off offset:16
	v_mul_f32_e32 v116, v119, v119
	v_mul_f32_e32 v117, v121, v121
	v_mul_f32_e32 v128, v115, v115
	v_fmac_f32_e32 v116, v118, v118
	v_fmac_f32_e32 v117, v120, v120
	v_mul_f32_e32 v129, v127, v127
	v_fmac_f32_e32 v128, v114, v114
	v_add_f32_e32 v116, v116, v117
	v_fmac_f32_e32 v129, v126, v126
	v_add_f32_e32 v116, v116, v128
	v_add_f32_e32 v116, v129, v116
	v_add_f32_e32 v116, v157, v116
	ds_bpermute_b32 v117, v125, v116
	v_cndmask_b32_e32 v128, v150, v124, vcc
	v_cvt_pk_bf16_f32 v118, v118, v119
	v_cvt_pk_bf16_f32 v119, v120, v121
	v_cvt_pk_bf16_f32 v120, v114, v115
	s_waitcnt lgkmcnt(0)
	v_add_f32_e32 v114, v116, v117
	v_lshlrev_b32_e32 v116, 2, v128
	ds_bpermute_b32 v115, v116, v114
	v_cvt_pk_bf16_f32 v121, v126, v127
	v_lshl_add_u64 v[126:127], s[8:9], 0, v[166:167]
	global_store_dwordx4 v[126:127], v[118:121], off
	s_and_saveexec_b64 s[22:23], s[0:1]
	s_cbranch_execz .LBB0_1522
	v_lshl_add_u64 v[118:119], v[148:149], 2, s[4:5]
	s_waitcnt lgkmcnt(0)
	v_add_f32_e32 v114, v114, v115
	global_atomic_add_f32 v[118:119], v114, off
.LBB0_1522:
	s_or_b64 exec, exec, s[22:23]
	v_or_b32_e32 v114, 16, v148
	s_waitcnt lgkmcnt(0)
	v_ashrrev_i32_e32 v115, 31, v114
	v_lshlrev_b64 v[118:119], 11, v[114:115]
	v_readlane_b32 s48, v254, 9
	v_lshl_add_u64 v[158:159], v[118:119], 0, v[146:147]
	v_readlane_b32 s49, v254, 10
	v_readlane_b32 s50, v254, 11
	v_readlane_b32 s51, v254, 12
	v_lshl_add_u64 v[160:161], v[158:159], 2, s[48:49]
	v_lshlrev_b64 v[158:159], 1, v[158:159]
	v_lshl_add_u64 v[162:163], s[8:9], 0, v[158:159]
	v_or_b32_e32 v158, 0x100, v158
	v_readlane_b32 s52, v254, 13
	v_readlane_b32 s53, v254, 14
	v_readlane_b32 s54, v254, 15
	v_readlane_b32 s55, v254, 16
	v_readlane_b32 s56, v254, 17
	v_readlane_b32 s57, v254, 18
	v_readlane_b32 s58, v254, 19
	v_readlane_b32 s59, v254, 20
	v_readlane_b32 s60, v254, 21
	v_readlane_b32 s61, v254, 22
	v_readlane_b32 s62, v254, 23
	v_readlane_b32 s63, v254, 24
	s_waitcnt vmcnt(8)
	v_pk_add_f32 v[120:121], v[112:113], v[194:195]
	v_pk_add_f32 v[118:119], v[110:111], v[192:193]
	v_pk_add_f32 v[128:129], v[108:109], v[198:199]
	v_pk_add_f32 v[126:127], v[106:107], v[196:197]
	v_cvt_pk_bf16_f32 v106, v118, v119
	v_cvt_pk_bf16_f32 v107, v120, v121
	v_mul_f32_e32 v117, v119, v119
	v_cvt_pk_bf16_f32 v108, v126, v127
	v_cvt_pk_bf16_f32 v109, v128, v129
	global_store_dwordx4 v[162:163], v[106:109], off
	s_nop 1
	s_nop 0
	v_mul_f32_e32 v119, v121, v121
	v_mul_f32_e32 v121, v127, v127
	v_fmac_f32_e32 v117, v118, v118
	v_fmac_f32_e32 v119, v120, v120
	v_mul_f32_e32 v127, v129, v129
	v_fmac_f32_e32 v121, v126, v126
	v_add_f32_e32 v117, v117, v119
	v_fmac_f32_e32 v127, v128, v128
	v_add_f32_e32 v117, v117, v121
	v_add_f32_e32 v117, v127, v117
	v_pk_add_f32 v[104:105], v[104:105], v[202:203]
	v_pk_add_f32 v[102:103], v[102:103], v[200:201]
	v_pk_add_f32 v[106:107], v[100:101], v[206:207]
	v_pk_add_f32 v[98:99], v[98:99], v[204:205]
	global_load_dwordx4 v[192:195], v[208:209], off offset:512
	global_load_dwordx4 v[196:199], v[208:209], off offset:528
	v_lshl_add_u64 v[208:209], v[208:209], 0, s[100:101]
	global_load_dwordx4 v[200:203], v[208:209], off
	global_load_dwordx4 v[204:207], v[208:209], off offset:16
	v_mul_f32_e32 v100, v103, v103
	v_mul_f32_e32 v101, v105, v105
	v_mul_f32_e32 v108, v99, v99
	v_fmac_f32_e32 v100, v102, v102
	v_fmac_f32_e32 v101, v104, v104
	v_mul_f32_e32 v109, v107, v107
	v_fmac_f32_e32 v108, v98, v98
	v_add_f32_e32 v100, v100, v101
	v_add_f32_e32 v100, v100, v108
	v_fmac_f32_e32 v109, v106, v106
	v_add_f32_e32 v100, v109, v100
	v_add_f32_e32 v108, v117, v100
	ds_bpermute_b32 v109, v125, v108
	v_cvt_pk_bf16_f32 v100, v102, v103
	v_cvt_pk_bf16_f32 v101, v104, v105
	v_cvt_pk_bf16_f32 v102, v98, v99
	v_lshl_add_u64 v[104:105], s[8:9], 0, v[158:159]
	s_waitcnt lgkmcnt(0)
	v_add_f32_e32 v98, v108, v109
	ds_bpermute_b32 v99, v116, v98
	v_cvt_pk_bf16_f32 v103, v106, v107
	global_store_dwordx4 v[104:105], v[100:103], off
	s_and_saveexec_b64 s[22:23], s[0:1]
	s_cbranch_execz .LBB0_1524
	v_lshl_add_u64 v[100:101], v[114:115], 2, s[4:5]
	s_waitcnt lgkmcnt(0)
	v_add_f32_e32 v98, v98, v99
	global_atomic_add_f32 v[100:101], v98, off
.LBB0_1524:
	s_or_b64 exec, exec, s[22:23]
	v_or_b32_e32 v98, 32, v148
	s_waitcnt lgkmcnt(0)
	v_ashrrev_i32_e32 v99, 31, v98
	v_lshlrev_b64 v[100:101], 11, v[98:99]
	v_readlane_b32 s48, v254, 9
	v_lshl_add_u64 v[108:109], v[100:101], 0, v[146:147]
	v_readlane_b32 s49, v254, 10
	v_readlane_b32 s50, v254, 11
	v_readlane_b32 s51, v254, 12
	v_lshl_add_u64 v[110:111], v[108:109], 2, s[48:49]
	v_lshlrev_b64 v[108:109], 1, v[108:109]
	v_lshl_add_u64 v[112:113], s[8:9], 0, v[108:109]
	v_or_b32_e32 v108, 0x100, v108
	v_readlane_b32 s52, v254, 13
	v_readlane_b32 s53, v254, 14
	v_readlane_b32 s54, v254, 15
	v_readlane_b32 s55, v254, 16
	v_readlane_b32 s56, v254, 17
	v_readlane_b32 s57, v254, 18
	v_readlane_b32 s58, v254, 19
	v_readlane_b32 s59, v254, 20
	v_readlane_b32 s60, v254, 21
	v_readlane_b32 s61, v254, 22
	v_readlane_b32 s62, v254, 23
	v_readlane_b32 s63, v254, 24
	s_waitcnt vmcnt(9)
	v_pk_add_f32 v[102:103], v[96:97], v[216:217]
	v_pk_add_f32 v[100:101], v[94:95], v[214:215]
	v_pk_add_f32 v[106:107], v[92:93], v[220:221]
	v_pk_add_f32 v[104:105], v[90:91], v[218:219]
	v_cvt_pk_bf16_f32 v90, v100, v101
	v_cvt_pk_bf16_f32 v91, v102, v103
	v_mul_f32_e32 v101, v101, v101
	v_cvt_pk_bf16_f32 v92, v104, v105
	v_cvt_pk_bf16_f32 v93, v106, v107
	global_store_dwordx4 v[112:113], v[90:93], off
	s_nop 1
	s_nop 0
	v_mul_f32_e32 v103, v103, v103
	v_mul_f32_e32 v105, v105, v105
	v_fmac_f32_e32 v101, v100, v100
	v_fmac_f32_e32 v103, v102, v102
	v_mul_f32_e32 v107, v107, v107
	v_fmac_f32_e32 v105, v104, v104
	v_add_f32_e32 v100, v101, v103
	v_fmac_f32_e32 v107, v106, v106
	v_add_f32_e32 v100, v100, v105
	v_add_f32_e32 v100, v107, v100
	v_pk_add_f32 v[88:89], v[88:89], v[178:179]
	v_pk_add_f32 v[86:87], v[86:87], v[176:177]
	v_pk_add_f32 v[90:91], v[84:85], v[182:183]
	v_pk_add_f32 v[82:83], v[82:83], v[180:181]
	global_load_dwordx4 v[214:217], v[208:209], off offset:512
	global_load_dwordx4 v[218:221], v[208:209], off offset:528
	v_lshl_add_u64 v[208:209], v[208:209], 0, s[98:99]
	global_load_dwordx4 v[176:179], v[208:209], off
	global_load_dwordx4 v[180:183], v[208:209], off offset:16
	v_mul_f32_e32 v84, v87, v87
	v_mul_f32_e32 v85, v89, v89
	v_mul_f32_e32 v92, v83, v83
	v_fmac_f32_e32 v84, v86, v86
	v_fmac_f32_e32 v85, v88, v88
	v_mul_f32_e32 v93, v91, v91
	v_fmac_f32_e32 v92, v82, v82
	v_add_f32_e32 v84, v84, v85
	v_add_f32_e32 v84, v84, v92
	v_fmac_f32_e32 v93, v90, v90
	v_add_f32_e32 v84, v93, v84
	v_add_f32_e32 v92, v100, v84
	ds_bpermute_b32 v93, v125, v92
	v_cvt_pk_bf16_f32 v84, v86, v87
	v_cvt_pk_bf16_f32 v85, v88, v89
	v_cvt_pk_bf16_f32 v86, v82, v83
	v_lshl_add_u64 v[88:89], s[8:9], 0, v[108:109]
	s_waitcnt lgkmcnt(0)
	v_add_f32_e32 v82, v92, v93
	ds_bpermute_b32 v83, v116, v82
	v_cvt_pk_bf16_f32 v87, v90, v91
	global_store_dwordx4 v[88:89], v[84:87], off
	s_and_saveexec_b64 s[22:23], s[0:1]
	v_readlane_b32 s52, v255, 15
	s_mov_b32 s84, s52
	v_readlane_b32 s53, v255, 16
	s_cbranch_execz .LBB0_1526
	v_lshl_add_u64 v[84:85], v[98:99], 2, s[4:5]
	s_waitcnt lgkmcnt(0)
	v_add_f32_e32 v82, v82, v83
	global_atomic_add_f32 v[84:85], v82, off
.LBB0_1526:
	s_or_b64 exec, exec, s[22:23]
	v_or_b32_e32 v82, 48, v148
	s_waitcnt lgkmcnt(0)
	v_ashrrev_i32_e32 v83, 31, v82
	v_lshlrev_b64 v[84:85], 11, v[82:83]
	v_readlane_b32 s56, v254, 9
	v_lshl_add_u64 v[92:93], v[84:85], 0, v[146:147]
	v_readlane_b32 s57, v254, 10
	v_readlane_b32 s58, v254, 11
	v_readlane_b32 s59, v254, 12
	v_lshl_add_u64 v[94:95], v[92:93], 2, s[56:57]
	v_lshlrev_b64 v[92:93], 1, v[92:93]
	v_lshl_add_u64 v[96:97], s[8:9], 0, v[92:93]
	v_or_b32_e32 v92, 0x100, v92
	v_readlane_b32 s60, v254, 13
	v_readlane_b32 s61, v254, 14
	v_readlane_b32 s62, v254, 15
	v_readlane_b32 s63, v254, 16
	v_readlane_b32 s64, v254, 17
	v_readlane_b32 s65, v254, 18
	v_readlane_b32 s66, v254, 19
	v_readlane_b32 s67, v254, 20
	v_readlane_b32 s68, v254, 21
	v_readlane_b32 s69, v254, 22
	v_readlane_b32 s70, v254, 23
	v_readlane_b32 s71, v254, 24
	s_waitcnt vmcnt(9)
	v_pk_add_f32 v[86:87], v[80:81], v[186:187]
	v_pk_add_f32 v[84:85], v[78:79], v[184:185]
	v_pk_add_f32 v[90:91], v[76:77], v[190:191]
	v_pk_add_f32 v[88:89], v[74:75], v[188:189]
	v_cvt_pk_bf16_f32 v74, v84, v85
	v_cvt_pk_bf16_f32 v75, v86, v87
	v_mul_f32_e32 v85, v85, v85
	v_cvt_pk_bf16_f32 v76, v88, v89
	v_cvt_pk_bf16_f32 v77, v90, v91
	global_store_dwordx4 v[96:97], v[74:77], off
	s_nop 1
	s_nop 0
	v_mul_f32_e32 v87, v87, v87
	v_mul_f32_e32 v89, v89, v89
	v_fmac_f32_e32 v85, v84, v84
	v_fmac_f32_e32 v87, v86, v86
	v_mul_f32_e32 v91, v91, v91
	v_fmac_f32_e32 v89, v88, v88
	v_add_f32_e32 v84, v85, v87
	v_fmac_f32_e32 v91, v90, v90
	v_add_f32_e32 v84, v84, v89
	v_add_f32_e32 v84, v91, v84
	v_pk_add_f32 v[72:73], v[72:73], v[194:195]
	v_pk_add_f32 v[70:71], v[70:71], v[192:193]
	v_pk_add_f32 v[74:75], v[68:69], v[198:199]
	v_pk_add_f32 v[66:67], v[66:67], v[196:197]
	global_load_dwordx4 v[184:187], v[208:209], off offset:512
	global_load_dwordx4 v[188:191], v[208:209], off offset:528
	v_lshl_add_u64 v[208:209], v[208:209], 0, s[98:99]
	global_load_dwordx4 v[192:195], v[208:209], off
	global_load_dwordx4 v[196:199], v[208:209], off offset:16
	v_mul_f32_e32 v68, v71, v71
	v_mul_f32_e32 v69, v73, v73
	v_mul_f32_e32 v76, v67, v67
	v_fmac_f32_e32 v68, v70, v70
	v_fmac_f32_e32 v69, v72, v72
	v_mul_f32_e32 v77, v75, v75
	v_fmac_f32_e32 v76, v66, v66
	v_add_f32_e32 v68, v68, v69
	v_add_f32_e32 v68, v68, v76
	v_fmac_f32_e32 v77, v74, v74
	v_add_f32_e32 v68, v77, v68
	v_add_f32_e32 v76, v84, v68
	ds_bpermute_b32 v77, v125, v76
	v_cvt_pk_bf16_f32 v68, v70, v71
	v_cvt_pk_bf16_f32 v69, v72, v73
	v_cvt_pk_bf16_f32 v70, v66, v67
	v_lshl_add_u64 v[72:73], s[8:9], 0, v[92:93]
	s_waitcnt lgkmcnt(0)
	v_add_f32_e32 v66, v76, v77
	ds_bpermute_b32 v67, v116, v66
	v_cvt_pk_bf16_f32 v71, v74, v75
	global_store_dwordx4 v[72:73], v[68:71], off
	s_and_saveexec_b64 s[22:23], s[0:1]
	s_cbranch_execz .LBB0_1528
	v_lshl_add_u64 v[68:69], v[82:83], 2, s[4:5]
	s_waitcnt lgkmcnt(0)
	v_add_f32_e32 v66, v66, v67
	global_atomic_add_f32 v[68:69], v66, off
.LBB0_1528:
	s_or_b64 exec, exec, s[22:23]
	v_add_u32_e32 v66, 0x80, v148
	s_waitcnt lgkmcnt(0)
	v_ashrrev_i32_e32 v67, 31, v66
	v_lshlrev_b64 v[68:69], 11, v[66:67]
	v_readlane_b32 s56, v254, 9
	v_lshl_add_u64 v[76:77], v[68:69], 0, v[146:147]
	v_readlane_b32 s57, v254, 10
	v_readlane_b32 s58, v254, 11
	v_readlane_b32 s59, v254, 12
	v_lshl_add_u64 v[78:79], v[76:77], 2, s[56:57]
	v_lshlrev_b64 v[76:77], 1, v[76:77]
	v_lshl_add_u64 v[80:81], s[8:9], 0, v[76:77]
	v_or_b32_e32 v76, 0x100, v76
	v_readlane_b32 s60, v254, 13
	v_readlane_b32 s61, v254, 14
	v_readlane_b32 s62, v254, 15
	v_readlane_b32 s63, v254, 16
	v_readlane_b32 s64, v254, 17
	v_readlane_b32 s65, v254, 18
	v_readlane_b32 s66, v254, 19
	v_readlane_b32 s67, v254, 20
	v_readlane_b32 s68, v254, 21
	v_readlane_b32 s69, v254, 22
	v_readlane_b32 s70, v254, 23
	v_readlane_b32 s71, v254, 24
	s_waitcnt vmcnt(9)
	v_pk_add_f32 v[70:71], v[64:65], v[202:203]
	v_pk_add_f32 v[68:69], v[62:63], v[200:201]
	v_pk_add_f32 v[74:75], v[60:61], v[206:207]
	v_pk_add_f32 v[72:73], v[58:59], v[204:205]
	v_cvt_pk_bf16_f32 v58, v68, v69
	v_cvt_pk_bf16_f32 v59, v70, v71
	v_mul_f32_e32 v69, v69, v69
	v_cvt_pk_bf16_f32 v60, v72, v73
	v_cvt_pk_bf16_f32 v61, v74, v75
	global_store_dwordx4 v[80:81], v[58:61], off
	s_nop 1
	s_nop 0
	v_mul_f32_e32 v71, v71, v71
	v_mul_f32_e32 v73, v73, v73
	v_fmac_f32_e32 v69, v68, v68
	v_fmac_f32_e32 v71, v70, v70
	v_mul_f32_e32 v75, v75, v75
	v_fmac_f32_e32 v73, v72, v72
	v_add_f32_e32 v68, v69, v71
	v_fmac_f32_e32 v75, v74, v74
	v_add_f32_e32 v68, v68, v73
	v_add_f32_e32 v68, v75, v68
	v_pk_add_f32 v[56:57], v[56:57], v[216:217]
	v_pk_add_f32 v[54:55], v[54:55], v[214:215]
	v_pk_add_f32 v[58:59], v[52:53], v[220:221]
	v_pk_add_f32 v[50:51], v[50:51], v[218:219]
	global_load_dwordx4 v[200:203], v[208:209], off offset:512
	global_load_dwordx4 v[204:207], v[208:209], off offset:528
	v_lshl_add_u64 v[208:209], v[208:209], 0, s[98:99]
	global_load_dwordx4 v[214:217], v[208:209], off
	global_load_dwordx4 v[218:221], v[208:209], off offset:16
	v_mul_f32_e32 v52, v55, v55
	v_mul_f32_e32 v53, v57, v57
	v_mul_f32_e32 v60, v51, v51
	v_fmac_f32_e32 v52, v54, v54
	v_fmac_f32_e32 v53, v56, v56
	v_mul_f32_e32 v61, v59, v59
	v_fmac_f32_e32 v60, v50, v50
	v_add_f32_e32 v52, v52, v53
	v_add_f32_e32 v52, v52, v60
	v_fmac_f32_e32 v61, v58, v58
	v_add_f32_e32 v52, v61, v52
	v_add_f32_e32 v60, v68, v52
	ds_bpermute_b32 v61, v125, v60
	v_cvt_pk_bf16_f32 v52, v54, v55
	v_cvt_pk_bf16_f32 v53, v56, v57
	v_cvt_pk_bf16_f32 v54, v50, v51
	v_lshl_add_u64 v[56:57], s[8:9], 0, v[76:77]
	s_waitcnt lgkmcnt(0)
	v_add_f32_e32 v50, v60, v61
	ds_bpermute_b32 v51, v116, v50
	v_cvt_pk_bf16_f32 v55, v58, v59
	global_store_dwordx4 v[56:57], v[52:55], off
	s_and_saveexec_b64 s[22:23], s[0:1]
	s_cbranch_execz .LBB0_1530
	v_lshl_add_u64 v[52:53], v[66:67], 2, s[4:5]
	s_waitcnt lgkmcnt(0)
	v_add_f32_e32 v50, v50, v51
	global_atomic_add_f32 v[52:53], v50, off
.LBB0_1530:
	s_or_b64 exec, exec, s[22:23]
	v_add_u32_e32 v50, 0x90, v148
	s_waitcnt lgkmcnt(0)
	v_ashrrev_i32_e32 v51, 31, v50
	v_lshlrev_b64 v[52:53], 11, v[50:51]
	v_readlane_b32 s56, v254, 9
	v_lshl_add_u64 v[60:61], v[52:53], 0, v[146:147]
	v_readlane_b32 s57, v254, 10
	v_readlane_b32 s58, v254, 11
	v_readlane_b32 s59, v254, 12
	v_lshl_add_u64 v[62:63], v[60:61], 2, s[56:57]
	v_lshlrev_b64 v[60:61], 1, v[60:61]
	v_lshl_add_u64 v[64:65], s[8:9], 0, v[60:61]
	v_or_b32_e32 v60, 0x100, v60
	v_readlane_b32 s60, v254, 13
	v_readlane_b32 s61, v254, 14
	v_readlane_b32 s62, v254, 15
	v_readlane_b32 s63, v254, 16
	v_readlane_b32 s64, v254, 17
	v_readlane_b32 s65, v254, 18
	v_readlane_b32 s66, v254, 19
	v_readlane_b32 s67, v254, 20
	v_readlane_b32 s68, v254, 21
	v_readlane_b32 s69, v254, 22
	v_readlane_b32 s70, v254, 23
	v_readlane_b32 s71, v254, 24
	s_waitcnt vmcnt(9)
	v_pk_add_f32 v[54:55], v[48:49], v[178:179]
	v_pk_add_f32 v[52:53], v[46:47], v[176:177]
	v_pk_add_f32 v[58:59], v[44:45], v[182:183]
	v_pk_add_f32 v[56:57], v[42:43], v[180:181]
	v_cvt_pk_bf16_f32 v42, v52, v53
	v_cvt_pk_bf16_f32 v43, v54, v55
	v_mul_f32_e32 v53, v53, v53
	v_cvt_pk_bf16_f32 v44, v56, v57
	v_cvt_pk_bf16_f32 v45, v58, v59
	global_store_dwordx4 v[64:65], v[42:45], off
	s_nop 1
	s_nop 0
	v_mul_f32_e32 v55, v55, v55
	v_mul_f32_e32 v57, v57, v57
	v_fmac_f32_e32 v53, v52, v52
	v_fmac_f32_e32 v55, v54, v54
	v_mul_f32_e32 v59, v59, v59
	v_fmac_f32_e32 v57, v56, v56
	v_add_f32_e32 v52, v53, v55
	v_fmac_f32_e32 v59, v58, v58
	v_add_f32_e32 v52, v52, v57
	v_add_f32_e32 v52, v59, v52
	v_pk_add_f32 v[40:41], v[40:41], v[186:187]
	v_pk_add_f32 v[38:39], v[38:39], v[184:185]
	v_pk_add_f32 v[42:43], v[36:37], v[190:191]
	v_pk_add_f32 v[34:35], v[34:35], v[188:189]
	global_load_dwordx4 v[176:179], v[208:209], off offset:512
	global_load_dwordx4 v[180:183], v[208:209], off offset:528
	v_mul_f32_e32 v36, v39, v39
	v_mul_f32_e32 v37, v41, v41
	v_mul_f32_e32 v44, v35, v35
	v_fmac_f32_e32 v36, v38, v38
	v_fmac_f32_e32 v37, v40, v40
	v_mul_f32_e32 v45, v43, v43
	v_fmac_f32_e32 v44, v34, v34
	v_add_f32_e32 v36, v36, v37
	v_add_f32_e32 v36, v36, v44
	v_fmac_f32_e32 v45, v42, v42
	v_add_f32_e32 v36, v45, v36
	v_add_f32_e32 v44, v52, v36
	ds_bpermute_b32 v45, v125, v44
	v_cvt_pk_bf16_f32 v36, v38, v39
	v_cvt_pk_bf16_f32 v37, v40, v41
	v_cvt_pk_bf16_f32 v38, v34, v35
	v_lshl_add_u64 v[40:41], s[8:9], 0, v[60:61]
	s_waitcnt lgkmcnt(0)
	v_add_f32_e32 v34, v44, v45
	ds_bpermute_b32 v35, v116, v34
	v_cvt_pk_bf16_f32 v39, v42, v43
	global_store_dwordx4 v[40:41], v[36:39], off
	s_and_saveexec_b64 s[22:23], s[0:1]
	s_cbranch_execz .LBB0_1532
	v_lshl_add_u64 v[36:37], v[50:51], 2, s[4:5]
	s_waitcnt lgkmcnt(0)
	v_add_f32_e32 v34, v34, v35
	global_atomic_add_f32 v[36:37], v34, off
.LBB0_1532:
	s_or_b64 exec, exec, s[22:23]
	v_add_u32_e32 v34, 0xa0, v148
	s_waitcnt lgkmcnt(0)
	v_ashrrev_i32_e32 v35, 31, v34
	v_lshlrev_b64 v[36:37], 11, v[34:35]
	v_readlane_b32 s56, v254, 9
	v_lshl_add_u64 v[44:45], v[36:37], 0, v[146:147]
	v_readlane_b32 s57, v254, 10
	v_readlane_b32 s58, v254, 11
	v_readlane_b32 s59, v254, 12
	v_lshl_add_u64 v[46:47], v[44:45], 2, s[56:57]
	v_lshlrev_b64 v[44:45], 1, v[44:45]
	v_lshl_add_u64 v[48:49], s[8:9], 0, v[44:45]
	v_or_b32_e32 v44, 0x100, v44
	v_readlane_b32 s60, v254, 13
	v_readlane_b32 s61, v254, 14
	v_readlane_b32 s62, v254, 15
	v_readlane_b32 s63, v254, 16
	v_readlane_b32 s64, v254, 17
	v_readlane_b32 s65, v254, 18
	v_readlane_b32 s66, v254, 19
	v_readlane_b32 s67, v254, 20
	v_readlane_b32 s68, v254, 21
	v_readlane_b32 s69, v254, 22
	v_readlane_b32 s70, v254, 23
	v_readlane_b32 s71, v254, 24
	s_waitcnt vmcnt(7)
	v_pk_add_f32 v[38:39], v[32:33], v[194:195]
	v_pk_add_f32 v[36:37], v[30:31], v[192:193]
	v_pk_add_f32 v[42:43], v[28:29], v[198:199]
	v_pk_add_f32 v[40:41], v[26:27], v[196:197]
	v_cvt_pk_bf16_f32 v26, v36, v37
	v_cvt_pk_bf16_f32 v27, v38, v39
	v_mul_f32_e32 v37, v37, v37
	v_cvt_pk_bf16_f32 v28, v40, v41
	v_cvt_pk_bf16_f32 v29, v42, v43
	global_store_dwordx4 v[48:49], v[26:29], off
	s_nop 1
	s_nop 0
	v_mul_f32_e32 v39, v39, v39
	v_mul_f32_e32 v41, v41, v41
	v_fmac_f32_e32 v37, v36, v36
	v_fmac_f32_e32 v39, v38, v38
	v_mul_f32_e32 v43, v43, v43
	v_fmac_f32_e32 v41, v40, v40
	v_add_f32_e32 v36, v37, v39
	v_fmac_f32_e32 v43, v42, v42
	v_add_f32_e32 v36, v36, v41
	v_add_f32_e32 v36, v43, v36
	v_pk_add_f32 v[24:25], v[24:25], v[202:203]
	v_pk_add_f32 v[22:23], v[22:23], v[200:201]
	v_pk_add_f32 v[26:27], v[20:21], v[206:207]
	v_pk_add_f32 v[18:19], v[18:19], v[204:205]
	v_mul_f32_e32 v20, v23, v23
	v_mul_f32_e32 v21, v25, v25
	v_mul_f32_e32 v28, v19, v19
	v_fmac_f32_e32 v20, v22, v22
	v_fmac_f32_e32 v21, v24, v24
	v_mul_f32_e32 v29, v27, v27
	v_fmac_f32_e32 v28, v18, v18
	v_add_f32_e32 v20, v20, v21
	v_add_f32_e32 v20, v20, v28
	v_fmac_f32_e32 v29, v26, v26
	v_add_f32_e32 v20, v29, v20
	v_add_f32_e32 v28, v36, v20
	ds_bpermute_b32 v29, v125, v28
	v_cvt_pk_bf16_f32 v20, v22, v23
	v_cvt_pk_bf16_f32 v21, v24, v25
	v_cvt_pk_bf16_f32 v22, v18, v19
	v_lshl_add_u64 v[24:25], s[8:9], 0, v[44:45]
	s_waitcnt lgkmcnt(0)
	v_add_f32_e32 v18, v28, v29
	ds_bpermute_b32 v19, v116, v18
	v_cvt_pk_bf16_f32 v23, v26, v27
	global_store_dwordx4 v[24:25], v[20:23], off
	s_and_saveexec_b64 s[22:23], s[0:1]
	s_cbranch_execz .LBB0_1534
	v_lshl_add_u64 v[20:21], v[34:35], 2, s[4:5]
	s_waitcnt lgkmcnt(0)
	v_add_f32_e32 v18, v18, v19
	global_atomic_add_f32 v[20:21], v18, off
.LBB0_1534:
	s_or_b64 exec, exec, s[22:23]
	v_add_u32_e32 v18, 0xb0, v148
	s_waitcnt lgkmcnt(0)
	v_ashrrev_i32_e32 v19, 31, v18
	v_lshlrev_b64 v[20:21], 11, v[18:19]
	v_readlane_b32 s56, v254, 9
	v_lshl_add_u64 v[28:29], v[20:21], 0, v[146:147]
	v_readlane_b32 s57, v254, 10
	v_readlane_b32 s58, v254, 11
	v_readlane_b32 s59, v254, 12
	v_lshl_add_u64 v[30:31], v[28:29], 2, s[56:57]
	v_lshlrev_b64 v[28:29], 1, v[28:29]
	v_lshl_add_u64 v[32:33], s[8:9], 0, v[28:29]
	v_or_b32_e32 v28, 0x100, v28
	v_readlane_b32 s60, v254, 13
	v_readlane_b32 s61, v254, 14
	v_readlane_b32 s62, v254, 15
	v_readlane_b32 s63, v254, 16
	v_readlane_b32 s64, v254, 17
	v_readlane_b32 s65, v254, 18
	v_readlane_b32 s66, v254, 19
	v_readlane_b32 s67, v254, 20
	v_readlane_b32 s68, v254, 21
	v_readlane_b32 s69, v254, 22
	v_readlane_b32 s70, v254, 23
	v_readlane_b32 s71, v254, 24
	s_waitcnt vmcnt(3)
	v_pk_add_f32 v[22:23], v[16:17], v[216:217]
	v_pk_add_f32 v[20:21], v[14:15], v[214:215]
	v_pk_add_f32 v[26:27], v[12:13], v[220:221]
	v_pk_add_f32 v[24:25], v[10:11], v[218:219]
	v_cvt_pk_bf16_f32 v10, v20, v21
	v_cvt_pk_bf16_f32 v11, v22, v23
	v_mul_f32_e32 v21, v21, v21
	v_cvt_pk_bf16_f32 v12, v24, v25
	v_cvt_pk_bf16_f32 v13, v26, v27
	global_store_dwordx4 v[32:33], v[10:13], off
	s_nop 1
	s_nop 0
	v_mul_f32_e32 v23, v23, v23
	v_mul_f32_e32 v25, v25, v25
	v_fmac_f32_e32 v21, v20, v20
	v_fmac_f32_e32 v23, v22, v22
	v_mul_f32_e32 v27, v27, v27
	v_fmac_f32_e32 v25, v24, v24
	v_add_f32_e32 v20, v21, v23
	v_fmac_f32_e32 v27, v26, v26
	v_add_f32_e32 v20, v20, v25
	v_add_f32_e32 v20, v27, v20
	v_pk_add_f32 v[8:9], v[8:9], v[178:179]
	v_pk_add_f32 v[6:7], v[6:7], v[176:177]
	v_pk_add_f32 v[10:11], v[4:5], v[182:183]
	v_pk_add_f32 v[2:3], v[2:3], v[180:181]
	v_mul_f32_e32 v4, v7, v7
	v_mul_f32_e32 v5, v9, v9
	v_mul_f32_e32 v12, v3, v3
	v_fmac_f32_e32 v4, v6, v6
	v_fmac_f32_e32 v5, v8, v8
	v_mul_f32_e32 v13, v11, v11
	v_fmac_f32_e32 v12, v2, v2
	v_add_f32_e32 v4, v4, v5
	v_add_f32_e32 v4, v4, v12
	v_fmac_f32_e32 v13, v10, v10
	v_add_f32_e32 v4, v13, v4
	v_add_f32_e32 v12, v20, v4
	ds_bpermute_b32 v13, v125, v12
	v_cvt_pk_bf16_f32 v4, v6, v7
	v_cvt_pk_bf16_f32 v5, v8, v9
	v_cvt_pk_bf16_f32 v6, v2, v3
	v_lshl_add_u64 v[8:9], s[8:9], 0, v[28:29]
	s_waitcnt lgkmcnt(0)
	v_add_f32_e32 v2, v12, v13
	ds_bpermute_b32 v3, v116, v2
	v_cvt_pk_bf16_f32 v7, v10, v11
	global_store_dwordx4 v[8:9], v[4:7], off
	s_and_saveexec_b64 s[22:23], s[0:1]
	s_cbranch_execz .LBB0_1536
	v_lshl_add_u64 v[4:5], v[18:19], 2, s[4:5]
	s_waitcnt lgkmcnt(0)
	v_add_f32_e32 v2, v2, v3
	global_atomic_add_f32 v[4:5], v2, off

	.amdhsa_kernel _Z9hymba_fwd4Args
		.amdhsa_group_segment_fixed_size 0
		.amdhsa_private_segment_fixed_size 0
		.amdhsa_kernarg_size 520
		.amdhsa_user_sgpr_count 2
		.amdhsa_user_sgpr_dispatch_ptr 0
		.amdhsa_user_sgpr_queue_ptr 0
		.amdhsa_user_sgpr_kernarg_segment_ptr 1
		.amdhsa_user_sgpr_dispatch_id 0
		.amdhsa_user_sgpr_kernarg_preload_length 0
		.amdhsa_user_sgpr_kernarg_preload_offset 0
		.amdhsa_user_sgpr_private_segment_size 0
		.amdhsa_uses_dynamic_stack 0
		.amdhsa_enable_private_segment 0
		.amdhsa_system_sgpr_workgroup_id_x 1
		.amdhsa_system_sgpr_workgroup_id_y 0
		.amdhsa_system_sgpr_workgroup_id_z 0
		.amdhsa_system_sgpr_workgroup_info 0
		.amdhsa_system_vgpr_workitem_id 0
		.amdhsa_next_free_vgpr 256
		.amdhsa_next_free_sgpr 102
		.amdhsa_accum_offset 256
		.amdhsa_reserve_vcc 1
		.amdhsa_float_round_mode_32 0
		.amdhsa_float_round_mode_16_64 0
		.amdhsa_float_denorm_mode_32 3
		.amdhsa_float_denorm_mode_16_64 3
		.amdhsa_dx10_clamp 1
		.amdhsa_ieee_mode 1
		.amdhsa_fp16_overflow 0
		.amdhsa_tg_split 0
		.amdhsa_exception_fp_ieee_invalid_op 0
		.amdhsa_exception_fp_denorm_src 0
		.amdhsa_exception_fp_ieee_div_zero 0
		.amdhsa_exception_fp_ieee_overflow 0
		.amdhsa_exception_fp_ieee_underflow 0
		.amdhsa_exception_fp_ieee_inexact 0
		.amdhsa_exception_int_div_zero 0
	.end_amdhsa_kernel

amdhsa.kernels:
  - .agpr_count:     0
    .args:
      - .offset:         0
        .size:           264
        .value_kind:     by_value
      - .offset:         264
        .size:           4
        .value_kind:     hidden_block_count_x
      - .offset:         268
        .size:           4
        .value_kind:     hidden_block_count_y
      - .offset:         272
        .size:           4
        .value_kind:     hidden_block_count_z
      - .offset:         276
        .size:           2
        .value_kind:     hidden_group_size_x
      - .offset:         278
        .size:           2
        .value_kind:     hidden_group_size_y
      - .offset:         280
        .size:           2
        .value_kind:     hidden_group_size_z
      - .offset:         282
        .size:           2
        .value_kind:     hidden_remainder_x
      - .offset:         284
        .size:           2
        .value_kind:     hidden_remainder_y
      - .offset:         286
        .size:           2
        .value_kind:     hidden_remainder_z
      - .offset:         304
        .size:           8
        .value_kind:     hidden_global_offset_x
      - .offset:         312
        .size:           8
        .value_kind:     hidden_global_offset_y
      - .offset:         320
        .size:           8
        .value_kind:     hidden_global_offset_z
      - .offset:         328
        .size:           2
        .value_kind:     hidden_grid_dims
      - .offset:         384
        .size:           4
        .value_kind:     hidden_dynamic_lds_size
    .group_segment_fixed_size: 0
    .kernarg_segment_align: 8
    .kernarg_segment_size: 520
    .language:       OpenCL C
    .language_version:
      - 2
      - 0
    .max_flat_workgroup_size: 512
    .name:           _Z9hymba_fwd4Args
    .private_segment_fixed_size: 0
    .sgpr_count:     108
    .sgpr_spill_count: 137
    .symbol:         _Z9hymba_fwd4Args.kd
    .uniform_work_group_size: 1
    .uses_dynamic_stack: false
    .vgpr_count:     256
    .vgpr_spill_count: 0
    .wavefront_size: 64
